# baseline (speedup 1.0000x reference)
; #define LAS __attribute__((address_space(3)))
; DI void ssd_prompt_unit(const Args& a, int b, int hd, LAS unsigned char* lds, const int tid) {
;     const int lane = tid & 63, wave = __builtin_amdgcn_readfirstlane(tid >> 6), gr = hd >> 3;
;     const bf16_t* HIN = (const bf16_t*)(a.ws + WS_HIN); bf16_t* MIX = (bf16_t*)(a.ws + WS_MIX);
;     const size_t row0 = (size_t)b * 2048;
;     LAS bf16_t* Cs = (LAS bf16_t*)(lds + SP_CS); LAS bf16_t* Cs2 = (LAS bf16_t*)(lds + SP_CS2); LAS bf16_t* Bs = (LAS bf16_t*)(lds + SP_BS);
;     LAS bf16_t* Bwt = (LAS bf16_t*)(lds + SP_BWT); LAS bf16_t* Xt = (LAS bf16_t*)(lds + SP_XT); LAS bf16_t* Hs = (LAS bf16_t*)(lds + SP_HS);
;     LAS float* cumS = (LAS float*)(lds + SP_CUM); LAS float* dtS = (LAS float*)(lds + SP_DT);
;     const float av = -__expf(a.in[19][hd]), dtb = a.in[18][hd], Dk = a.in[20][hd];
;     const int cgl = lane & 7, seg = lane >> 3, cg = wave < 4 ? wave * 8 + cgl : 32 + cgl, kq = wave < 4 ? 0 : wave - 4;
;     const bool stager = wave < 4;
;     const int typ = wave == 0 ? 0 : (wave < 3 ? 1 : 2);
;     int ch = 0;
;     if (cg < 8) ch = hd * 64 + cg * 8; else if (cg < 24) ch = 1024 + gr * 128 + (cg - 8) * 8; else ch = 1280 + gr * 128 + (cg - 24) * 8;
;     LAS float* cwS = (LAS float*)(lds + SP_CW) + cg * 40;
;     if (wave <= 4 && seg == 0) {
; #pragma unroll
;         for (int jj = 0; jj < 4; ++jj) { *(LAS f32x4*)(cwS + jj * 8) = *(const f32x4*)(a.in[16] + jj * 1536 + ch); *(LAS f32x4*)(cwS + jj * 8 + 4) = *(const f32x4*)(a.in[16] + jj * 1536 + ch + 4); }
;         *(LAS f32x4*)(cwS + 32) = *(const f32x4*)(a.in[17] + ch); *(LAS f32x4*)(cwS + 36) = *(const f32x4*)(a.in[17] + ch + 4);
;     }
;     u32x4 raw[11];
; #pragma unroll
;     for (int j = 0; j < 11; ++j) raw[j] = (u32x4){0u, 0u, 0u, 0u};
;     {
; #pragma unroll
;         for (int j = 0; j < 11; ++j) { const int t = seg * 8 - 3 + 2 * kq + (stager ? j : (j < 5 ? j : 4)); if (t >= 0) raw[j] = *(const u32x4*)(HIN + (row0 + t) * LDH + C_XBC + ch); }
;     }
;     for (int i = tid; i < 64 * SP_LDC / 2; i += NTHR) ((LAS unsigned*)Hs)[i] = 0u;
;     unsigned dtraw = 0u;
;     if (wave == 7) { ssd_dt_scan(ssd_dt_load(HIN, row0, hd, lane), dtb, av, lane, cumS, dtS); dtraw = ssd_dt_load(HIN, row0 + 64, hd, lane); }
;     f32x16 hacc[2];
; #pragma unroll
;     for (int i = 0; i < 16; ++i) { hacc[0][i] = 0.f; hacc[1][i] = 0.f; }
;     __syncthreads();
.LBB0_285:
	s_cmp_gt_i32 s70, 2
	s_cselect_b32 s0, 2, 1
	s_cmp_gt_u32 s4, 63
	s_cselect_b32 s67, s0, 0
	s_ashr_i32 s0, s64, 31
	s_and_b64 s[2:3], s[26:27], exec
	s_movk_i32 s2, 0x6a00
	s_cselect_b32 s10, s2, 0x3500
	s_movk_i32 s2, 0x7740
	s_cselect_b32 s11, s2, 0x3500
	s_mov_b32 s2, 0x8480
	s_cselect_b32 s12, s2, 0x3500
	v_lshlrev_b32_e32 v4, 2, v8
	s_add_i32 s2, 0, 0x1c200
	v_add_u32_e32 v219, s2, v4
	s_add_i32 s2, 0, 0x1c000
	v_add_u32_e32 v220, s2, v4
	s_lshl_b32 s2, s70, 1
	s_and_b32 s13, s2, 2
	s_lshl_b32 s17, s6, 4
	s_ashr_i32 s6, s4, 7
	s_lshl_b32 s2, s70, 5
	s_and_b32 s63, s2, 32
	s_lshl_b32 s2, s6, 6
	v_readlane_b32 s15, v253, 16
	s_and_b32 s18, s17, 0x7fffffe0
	s_lshl_b32 s69, s13, 5
	s_lshl_b32 s19, s6, 5
	s_add_i32 s71, s15, s2
	s_movk_i32 s2, 0x480
	s_mov_b32 s56, s24
	s_movk_i32 s24, 0x110
	v_mul_lo_u32 v223, v9, s2
	s_and_b64 s[2:3], s[26:27], exec
	v_mul_lo_u32 v221, v2, s24
	v_lshlrev_b32_e32 v2, 1, v2
	s_cselect_b32 s2, 2, s5
	v_add_u32_e32 v222, 0, v2
	v_add_u32_e32 v4, s15, v2
	v_add_u32_e32 v2, s2, v134
	v_mul_lo_u32 v226, v2, s24
	v_lshlrev_b32_e32 v2, 1, v2
	s_cselect_b32 s2, 4, s5
	v_add_u32_e32 v227, 0, v2
	v_add_u32_e32 v5, s15, v2
	v_add_u32_e32 v2, s2, v134
	v_mul_lo_u32 v229, v2, s24
	v_lshlrev_b32_e32 v2, 1, v2
	s_cselect_b32 s2, 6, s5
	s_lshl_b32 s61, s13, 6
	v_add_u32_e32 v230, 0, v2
	v_add_u32_e32 v6, s15, v2
	v_add_u32_e32 v2, s2, v134
	s_cmp_gt_i32 s6, -1
	v_mul_lo_u32 v232, v2, s24
	s_cselect_b64 s[24:25], -1, 0
	s_cmp_gt_i32 s6, 0
	v_lshl_add_u32 v218, v9, 4, 0
	s_cselect_b64 s[2:3], -1, 0
	s_add_u32 s6, s64, s30
	v_mov_b32_e32 v135, v161
	v_add_u32_e32 v3, 0xfffffe80, v218
	s_mul_i32 s14, s7, 0xd40
	v_lshlrev_b32_e32 v2, 1, v2
	s_addc_u32 s7, s0, s31
	v_add_u32_e32 v225, v3, v221
	v_add_u32_e32 v228, v3, v226
	v_add_u32_e32 v231, v3, v229
	v_add_u32_e32 v233, 0, v2
	v_add_u32_e32 v7, s15, v2
	v_add_u32_e32 v234, v3, v232
	v_lshl_add_u64 v[2:3], v[134:135], 0, s[6:7]
	s_mul_i32 s6, s90, 0x600000
	s_lshl_b32 s0, s60, 7
	v_lshl_add_u64 v[138:139], v[0:1], 1, s[82:83]
	s_or_b32 s6, s6, s0
	s_and_b32 s4, s4, 64
	v_readlane_b32 s72, v254, 20
	s_or_b32 s4, s6, s4
	v_readlane_b32 s86, v254, 34
	s_mul_hi_i32 s5, s90, 0x600000
	v_readlane_b32 s87, v254, 35
	s_add_u32 s59, s86, s4
	s_addc_u32 s65, s87, s5
	s_lshl_b32 s6, s60, 1
	v_readlane_b32 s7, v254, 62
	s_add_u32 s6, s7, s6
	v_readlane_b32 s7, v254, 63
	s_mul_i32 s4, s90, 0xd40000
	s_addc_u32 s7, s7, 0
	s_mul_hi_i32 s5, s90, 0xd40000
	s_add_u32 s4, s6, s4
	s_addc_u32 s5, s7, s5
	v_readlane_b32 s82, v254, 30
	v_readlane_b32 s83, v254, 31
	v_mov_b64_e32 v[0:1], s[4:5]
	v_mov_b32_e32 v160, v161
	v_cmp_eq_u32_e64 s[42:43], 0, v8
	v_cmp_gt_u32_e64 s[44:45], 2, v8
	v_cmp_gt_u32_e64 s[46:47], 4, v8
	v_cmp_gt_u32_e64 s[48:49], 16, v8
	v_cmp_gt_u32_e64 s[50:51], 32, v8
	s_mulk_i32 s9, 0xd40
	v_lshl_add_u64 v[136:137], v[2:3], 0, -3
	v_readlane_b32 s82, v254, 40
	v_mad_u64_u32 v[140:141], s[4:5], v8, s55, v[0:1]
	v_mov_b32_e32 v162, v161
	v_mov_b32_e32 v163, v161
	v_mov_b32_e32 v164, v161
	v_mov_b32_e32 v165, v161
	v_mov_b32_e32 v166, v161
	v_mov_b32_e32 v167, v161
	v_mov_b32_e32 v168, v161
	v_mov_b32_e32 v169, v161
	v_mov_b32_e32 v170, v161
	v_mov_b32_e32 v171, v161
	v_mov_b32_e32 v172, v161
	v_mov_b32_e32 v173, v161
	v_mov_b32_e32 v174, v161
	v_mov_b32_e32 v175, v161
	v_add_u32_e32 v135, v4, v223
	v_add_u32_e32 v235, v5, v223
	v_add_u32_e32 v236, v6, v223
	v_add_u32_e32 v237, v7, v223
	v_mov_b64_e32 v[0:1], v[160:161]
	v_mov_b64_e32 v[16:17], v[160:161]
	s_mov_b32 s1, 0
	v_add_u32_e32 v224, 0xffffdc00, v223
	s_mul_i32 s96, s8, 0x1a80
	s_mov_b32 s97, s95
	s_mov_b32 s62, 64
	v_readlane_b32 s83, v254, 41
	s_mov_b64 s[92:93], 0
	s_lshl_b32 s94, s14, 1
	s_lshl_b32 s4, s10, 1
	s_lshl_b32 s6, s11, 1
	s_lshl_b32 s8, s12, 1
	s_lshl_b32 s10, s9, 1
	v_mov_b64_e32 v[2:3], v[162:163]
	v_mov_b64_e32 v[4:5], v[164:165]
	v_mov_b64_e32 v[6:7], v[166:167]
	v_mov_b64_e32 v[8:9], v[168:169]
	v_mov_b64_e32 v[10:11], v[170:171]
	v_mov_b64_e32 v[12:13], v[172:173]
	v_mov_b64_e32 v[14:15], v[174:175]
	v_mov_b64_e32 v[18:19], v[162:163]
	v_mov_b64_e32 v[20:21], v[164:165]
	v_mov_b64_e32 v[22:23], v[166:167]
	v_mov_b64_e32 v[24:25], v[168:169]
	v_mov_b64_e32 v[26:27], v[170:171]
	v_mov_b64_e32 v[28:29], v[172:173]
	v_mov_b64_e32 v[30:31], v[174:175]
	s_waitcnt lgkmcnt(0)
	s_barrier
	v_readlane_b32 s73, v254, 21
	v_readlane_b32 s74, v254, 22
	v_readlane_b32 s75, v254, 23
	v_readlane_b32 s76, v254, 24
	v_readlane_b32 s77, v254, 25
	v_readlane_b32 s78, v254, 26
	v_readlane_b32 s79, v254, 27
	v_readlane_b32 s80, v254, 28
	v_readlane_b32 s81, v254, 29
	v_readlane_b32 s84, v254, 32
	v_readlane_b32 s85, v254, 33
	v_mov_b32_e32 v250, 0xbfb8aa3b
; #define LAS __attribute__((address_space(3)))
; DI void conv_row8(const u32x4 (&raw)[11], int i, const float (&w)[4][8], const float (&bias)[8], float (&v)[8]) {
; #pragma unroll
;     for (int e = 0; e < 8; ++e) v[e] = bias[e];
; #pragma unroll
;     for (int jj = 0; jj < 4; ++jj) {
; #pragma unroll
;         for (int e = 0; e < 4; ++e) { v[2 * e] += w[jj][2 * e] * lo16(raw[i + jj][e]); v[2 * e + 1] += w[jj][2 * e + 1] * hi16(raw[i + jj][e]); }
;     }
; #pragma unroll
;     for (int e = 0; e < 8; ++e) v[e] = v[e] * __frcp_rn(1.0f + __expf(-v[e]));
; }
; DI void ssd_prompt_unit(const Args& a, int b, int hd, LAS unsigned char* lds, const int tid) {
;     ...
;         const int buf = c & 1, t0 = c * 64;
;         LAS float* cumC = cumS + buf * 64; LAS float* dtC = dtS + buf * 64;
;         LAS bf16_t* HsC = Hs + buf * 64 * SP_LDC; LAS bf16_t* HsN = Hs + (buf ^ 1) * 64 * SP_LDC;
;         {
;             const float cum63 = cumC[63];
;             float cwt[4][8], cbias[8];
; #pragma unroll
;             for (int jj = 0; jj < 4; ++jj) { const f32x4 w0 = *(const LAS f32x4*)(cwS + jj * 8), w1 = *(const LAS f32x4*)(cwS + jj * 8 + 4);
; #pragma unroll
;                 for (int e = 0; e < 4; ++e) { cwt[jj][e] = w0[e]; cwt[jj][4 + e] = w1[e]; } }
;             { const f32x4 b0 = *(const LAS f32x4*)(cwS + 32), b1 = *(const LAS f32x4*)(cwS + 36);
; #pragma unroll
;               for (int e = 0; e < 4; ++e) { cbias[e] = b0[e]; cbias[4 + e] = b1[e]; } }
;             const f32x4 cq0 = *(const LAS f32x4*)(cumC + seg * 8), cq1 = *(const LAS f32x4*)(cumC + seg * 8 + 4), dq0 = *(const LAS f32x4*)(dtC + seg * 8), dq1 = *(const LAS f32x4*)(dtC + seg * 8 + 4);
;             const float cqa[8] = {cq0[0], cq0[1], cq0[2], cq0[3], cq1[0], cq1[1], cq1[2], cq1[3]}, dqa[8] = {dq0[0], dq0[1], dq0[2], dq0[3], dq1[0], dq1[1], dq1[2], dq1[3]};
;             const int tn = (c + 1 < 32) ? t0 + 64 : t0;
;             const bf16_t* nsrc = HIN + (row0 + tn + seg * 8 - 3 + 2 * kq) * LDH + C_XBC + ch;
;     ...
; #pragma unroll
;             for (int k = 0; k < 4; ++k) {
;                 const bool act = stager || k == 0;
;                 float va[8], vb[8];
;                 if (act) { conv_row8(raw, 2 * k, cwt, cbias, va); conv_row8(raw, 2 * k + 1, cwt, cbias, vb); }
;                 raw[2 * k] = *(const u32x4*)(nsrc + SP_ROWOFF(2 * k)); raw[2 * k + 1] = *(const u32x4*)(nsrc + SP_ROWOFF(2 * k + 1));
.LBB0_286:
	s_and_b32 s58, s1, 1
	s_lshl_b32 s5, s58, 8
	s_add_i32 s66, s5, 0
	s_add_i32 s57, s66, 0x1c000
	s_add_i32 s66, s66, 0x1c200
	s_cmp_lg_u32 s92, 0x5d0000
	s_cselect_b64 s[12:13], -1, 0
	v_mov_b32_e32 v32, s57
	s_and_b64 s[14:15], s[12:13], exec
	ds_read_b32 v160, v32 offset:252
	ds_read_b128 v[100:103], v215
	ds_read_b128 v[44:47], v215 offset:16
	ds_read_b128 v[104:107], v215 offset:32
	ds_read_b128 v[48:51], v215 offset:48
	ds_read_b128 v[108:111], v215 offset:64
	ds_read_b128 v[52:55], v215 offset:80
	ds_read_b128 v[60:63], v215 offset:96
	ds_read_b128 v[40:43], v215 offset:112
	ds_read_b128 v[112:115], v215 offset:128
	ds_read_b128 v[56:59], v215 offset:144
	s_cselect_b32 s14, s62, 0x7c0
	s_mov_b32 s15, s95
	v_lshl_add_u64 v[144:145], v[136:137], 0, s[14:15]
	v_mad_u64_u32 v[142:143], s[14:15], v144, s55, v[138:139]
	v_mad_i32_i24 v143, v145, s55, v143
	s_waitcnt vmcnt(0)
	v_lshlrev_b32_e32 v144, 16, v72
	v_and_b32_e32 v145, 0xffff0000, v72
	v_lshlrev_b32_e32 v148, 16, v73
	v_and_b32_e32 v149, 0xffff0000, v73
	v_lshlrev_b32_e32 v146, 16, v76
	v_and_b32_e32 v147, 0xffff0000, v76
	v_lshlrev_b32_e32 v150, 16, v77
	v_and_b32_e32 v151, 0xffff0000, v77
	v_lshlrev_b32_e32 v76, 16, v78
	v_and_b32_e32 v77, 0xffff0000, v78
	v_lshlrev_b32_e32 v72, 16, v79
	v_and_b32_e32 v73, 0xffff0000, v79
	s_waitcnt lgkmcnt(1)
	v_pk_fma_f32 v[78:79], v[100:101], v[144:145], v[112:113]
	v_lshlrev_b32_e32 v190, 16, v92
	v_and_b32_e32 v191, 0xffff0000, v92
	v_pk_fma_f32 v[78:79], v[104:105], v[146:147], v[78:79]
	v_lshlrev_b32_e32 v186, 16, v96
	v_and_b32_e32 v187, 0xffff0000, v96
	v_pk_fma_f32 v[78:79], v[108:109], v[190:191], v[78:79]
	v_lshlrev_b32_e32 v174, 16, v93
	v_pk_fma_f32 v[78:79], v[60:61], v[186:187], v[78:79]
	v_and_b32_e32 v175, 0xffff0000, v93
	v_lshlrev_b32_e32 v170, 16, v97
	v_and_b32_e32 v171, 0xffff0000, v97
	v_lshlrev_b32_e32 v96, 16, v98
	v_and_b32_e32 v97, 0xffff0000, v98
	v_lshlrev_b32_e32 v92, 16, v99
	v_and_b32_e32 v93, 0xffff0000, v99
	v_pk_mul_f32 v[98:99], v[78:79], v[250:251] op_sel_hi:[1,0]
	v_exp_f32_e32 v98, v98
	v_exp_f32_e32 v99, v99
	v_lshlrev_b32_e32 v152, 16, v122
	v_and_b32_e32 v153, 0xffff0000, v122
	v_lshlrev_b32_e32 v156, 16, v120
	v_pk_add_f32 v[98:99], v[98:99], 1.0 op_sel_hi:[1,0]
	v_and_b32_e32 v157, 0xffff0000, v120
	v_lshlrev_b32_e32 v154, 16, v121
	v_and_b32_e32 v155, 0xffff0000, v121
	v_lshlrev_b32_e32 v120, 16, v123
	v_and_b32_e32 v121, 0xffff0000, v123
	v_lshlrev_b32_e32 v158, 16, v74
	v_and_b32_e32 v159, 0xffff0000, v74
	v_lshlrev_b32_e32 v168, 16, v94
	v_rcp_f32_e32 v99, v99
	v_and_b32_e32 v169, 0xffff0000, v94
	v_lshlrev_b32_e32 v74, 16, v75
	v_and_b32_e32 v75, 0xffff0000, v75
	v_rcp_f32_e32 v98, v98
	s_nop 0
	v_pk_mul_f32 v[144:145], v[78:79], v[98:99]
	v_pk_fma_f32 v[78:79], v[100:101], v[146:147], v[112:113]
	s_waitcnt lgkmcnt(0)
	v_pk_fma_f32 v[74:75], v[46:47], v[74:75], v[58:59]
	v_pk_fma_f32 v[78:79], v[104:105], v[190:191], v[78:79]
	v_lshlrev_b32_e32 v94, 16, v95
	v_pk_fma_f32 v[78:79], v[108:109], v[186:187], v[78:79]
	v_and_b32_e32 v95, 0xffff0000, v95
	v_pk_fma_f32 v[78:79], v[60:61], v[156:157], v[78:79]
	v_pk_fma_f32 v[74:75], v[50:51], v[72:73], v[74:75]
	v_pk_mul_f32 v[98:99], v[78:79], v[250:251] op_sel_hi:[1,0]
	v_exp_f32_e32 v98, v98
	v_exp_f32_e32 v99, v99
	v_pk_fma_f32 v[74:75], v[54:55], v[94:95], v[74:75]
	v_pk_fma_f32 v[72:73], v[46:47], v[72:73], v[58:59]
	v_pk_fma_f32 v[74:75], v[42:43], v[92:93], v[74:75]
	v_pk_add_f32 v[98:99], v[98:99], 1.0 op_sel_hi:[1,0]
	v_pk_fma_f32 v[72:73], v[50:51], v[94:95], v[72:73]
	v_pk_fma_f32 v[72:73], v[54:55], v[92:93], v[72:73]
	v_lshlrev_b32_e32 v32, 2, v134
	v_pk_fma_f32 v[72:73], v[42:43], v[120:121], v[72:73]
	v_rcp_f32_e32 v99, v99
	v_add_u32_e32 v162, s57, v32
	v_add_u32_e32 v32, s66, v32
	ds_read_b128 v[128:131], v162
	ds_read_b128 v[36:39], v162 offset:16
	v_rcp_f32_e32 v98, v98
	s_nop 0
	v_pk_mul_f32 v[146:147], v[78:79], v[98:99]
	v_pk_fma_f32 v[78:79], v[102:103], v[148:149], v[114:115]
	ds_read_b128 v[124:127], v32
	ds_read_b128 v[32:35], v32 offset:16
	v_pk_fma_f32 v[78:79], v[106:107], v[150:151], v[78:79]
	s_cmp_lt_i32 s67, 1
	v_pk_fma_f32 v[78:79], v[110:111], v[174:175], v[78:79]
	v_pk_fma_f32 v[78:79], v[62:63], v[170:171], v[78:79]
	v_pk_mul_f32 v[98:99], v[78:79], v[250:251] op_sel_hi:[1,0]
	v_exp_f32_e32 v98, v98
	v_exp_f32_e32 v99, v99
	s_nop 0
	v_pk_add_f32 v[98:99], v[98:99], 1.0 op_sel_hi:[1,0]
	v_rcp_f32_e32 v99, v99
	v_rcp_f32_e32 v98, v98
	s_nop 0
	v_pk_mul_f32 v[148:149], v[78:79], v[98:99]
	v_pk_fma_f32 v[78:79], v[102:103], v[150:151], v[114:115]
	v_pk_fma_f32 v[78:79], v[106:107], v[174:175], v[78:79]
	v_pk_fma_f32 v[78:79], v[110:111], v[170:171], v[78:79]
	v_pk_fma_f32 v[78:79], v[62:63], v[154:155], v[78:79]
	v_pk_mul_f32 v[98:99], v[78:79], v[250:251] op_sel_hi:[1,0]
	v_exp_f32_e32 v98, v98
	v_exp_f32_e32 v99, v99
	s_nop 0
	v_pk_add_f32 v[98:99], v[98:99], 1.0 op_sel_hi:[1,0]
	v_rcp_f32_e32 v99, v99
	v_rcp_f32_e32 v98, v98
	s_nop 0
	v_pk_mul_f32 v[150:151], v[78:79], v[98:99]
	v_pk_fma_f32 v[78:79], v[44:45], v[158:159], v[56:57]
	v_pk_fma_f32 v[78:79], v[48:49], v[76:77], v[78:79]
	v_pk_fma_f32 v[76:77], v[44:45], v[76:77], v[56:57]
	v_pk_fma_f32 v[78:79], v[52:53], v[168:169], v[78:79]
	v_pk_fma_f32 v[76:77], v[48:49], v[168:169], v[76:77]
	v_pk_fma_f32 v[78:79], v[40:41], v[96:97], v[78:79]
	v_pk_fma_f32 v[76:77], v[52:53], v[96:97], v[76:77]
	v_pk_mul_f32 v[98:99], v[78:79], v[250:251] op_sel_hi:[1,0]
	v_exp_f32_e32 v98, v98
	v_exp_f32_e32 v99, v99
	v_pk_fma_f32 v[76:77], v[40:41], v[152:153], v[76:77]
	v_pk_add_f32 v[98:99], v[98:99], 1.0 op_sel_hi:[1,0]
	v_rcp_f32_e32 v99, v99
	v_rcp_f32_e32 v98, v98
	s_nop 0
	v_pk_mul_f32 v[158:159], v[78:79], v[98:99]
	v_pk_mul_f32 v[78:79], v[76:77], v[250:251] op_sel_hi:[1,0]
	v_exp_f32_e32 v78, v78
	v_exp_f32_e32 v79, v79
	s_nop 0
	v_pk_add_f32 v[78:79], v[78:79], 1.0 op_sel_hi:[1,0]
	v_rcp_f32_e32 v79, v79
	v_rcp_f32_e32 v78, v78
	s_nop 0
	v_pk_mul_f32 v[166:167], v[76:77], v[78:79]
	v_pk_mul_f32 v[76:77], v[74:75], v[250:251] op_sel_hi:[1,0]
	v_exp_f32_e32 v76, v76
	v_exp_f32_e32 v77, v77
	s_nop 0
	v_pk_add_f32 v[76:77], v[76:77], 1.0 op_sel_hi:[1,0]
	v_rcp_f32_e32 v77, v77
	v_rcp_f32_e32 v76, v76
	s_nop 0
	v_pk_mul_f32 v[184:185], v[74:75], v[76:77]
	v_pk_mul_f32 v[74:75], v[72:73], v[250:251] op_sel_hi:[1,0]
	v_exp_f32_e32 v74, v74
	v_exp_f32_e32 v75, v75
	s_nop 0
	v_pk_add_f32 v[74:75], v[74:75], 1.0 op_sel_hi:[1,0]
	v_rcp_f32_e32 v75, v75
	s_mov_b64 s[14:15], -1
	v_rcp_f32_e32 v74, v74
	v_add_co_u32_e32 v76, vcc, 0x2000, v142
	v_pk_mul_f32 v[194:195], v[72:73], v[74:75]
	s_nop 0
	v_addc_co_u32_e32 v77, vcc, 0, v143, vcc
	global_load_dwordx4 v[72:75], v[142:143], off offset:3584
	s_nop 0
	global_load_dwordx4 v[76:79], v[76:77], off offset:2176
	s_cbranch_scc1 .LBB0_295
	s_cmp_lg_u32 s67, 1
	s_cbranch_scc0 .LBB0_292
	s_andn2_b64 vcc, exec, s[22:23]
	s_cbranch_vccnz .LBB0_290
	v_lshl_add_u32 v98, s64, 2, v162
	ds_read_b64 v[98:99], v98
	s_branch .LBB0_291

; DI float lo16(unsigned w) { return __uint_as_float(w << 16); }
; DI float hi16(unsigned w) { return __uint_as_float(w & 0xffff0000u); }
; DI void conv_row8(const u32x4 (&raw)[11], int i, const float (&w)[4][8], const float (&bias)[8], float (&v)[8]) {
; #pragma unroll
;     for (int e = 0; e < 8; ++e) v[e] = bias[e];
; #pragma unroll
;     for (int jj = 0; jj < 4; ++jj) {
; #pragma unroll
;         for (int e = 0; e < 4; ++e) { v[2 * e] += w[jj][2 * e] * lo16(raw[i + jj][e]); v[2 * e + 1] += w[jj][2 * e + 1] * hi16(raw[i + jj][e]); }
;     }
; #pragma unroll
;     for (int e = 0; e < 8; ++e) v[e] = v[e] * __frcp_rn(1.0f + __expf(-v[e]));
; }
; DI void ssd_prompt_unit(const Args& a, int b, int hd, LAS unsigned char* lds, const int tid) {
;     ...
;             for (int k = 0; k < 4; ++k) {
;                 const bool act = stager || k == 0;
;                 float va[8], vb[8];
;                 if (act) { conv_row8(raw, 2 * k, cwt, cbias, va); conv_row8(raw, 2 * k + 1, cwt, cbias, vb); }
;                 raw[2 * k] = *(const u32x4*)(nsrc + SP_ROWOFF(2 * k)); raw[2 * k + 1] = *(const u32x4*)(nsrc + SP_ROWOFF(2 * k + 1));
.LBB0_297:
	v_cndmask_b32_e64 v98, 0, 1, s[26:27]
	v_cmp_ne_u32_e64 s[52:53], 1, v98
	s_andn2_b64 vcc, exec, s[26:27]
	v_lshlrev_b32_e32 v192, 16, v80
	v_and_b32_e32 v193, 0xffff0000, v80
	v_lshlrev_b32_e32 v164, 16, v116
	v_and_b32_e32 v165, 0xffff0000, v116
	v_lshlrev_b32_e32 v188, 16, v81
	v_and_b32_e32 v189, 0xffff0000, v81
	v_lshlrev_b32_e32 v162, 16, v117
	v_and_b32_e32 v163, 0xffff0000, v117
	v_lshlrev_b32_e32 v172, 16, v82
	v_and_b32_e32 v173, 0xffff0000, v82
	s_waitcnt lgkmcnt(3)
	v_lshlrev_b32_e32 v128, 16, v118
	v_and_b32_e32 v129, 0xffff0000, v118
	v_lshlrev_b32_e32 v122, 16, v83
	v_and_b32_e32 v123, 0xffff0000, v83
	s_waitcnt lgkmcnt(1)
	v_lshlrev_b32_e32 v124, 16, v119
	v_and_b32_e32 v125, 0xffff0000, v119
	s_cbranch_vccnz .LBB0_299
	v_pk_fma_f32 v[80:81], v[100:101], v[190:191], v[112:113]
	v_pk_fma_f32 v[80:81], v[104:105], v[186:187], v[80:81]
	v_pk_fma_f32 v[80:81], v[108:109], v[156:157], v[80:81]
	v_pk_fma_f32 v[80:81], v[60:61], v[192:193], v[80:81]
	v_pk_mul_f32 v[82:83], v[80:81], v[250:251] op_sel_hi:[1,0]
	v_exp_f32_e32 v82, v82
	v_exp_f32_e32 v83, v83
	s_nop 0
	v_pk_add_f32 v[82:83], v[82:83], 1.0 op_sel_hi:[1,0]
	v_rcp_f32_e32 v83, v83
	v_rcp_f32_e32 v82, v82
	s_nop 0
	v_pk_mul_f32 v[144:145], v[80:81], v[82:83]
	v_pk_fma_f32 v[80:81], v[100:101], v[186:187], v[112:113]
	v_pk_fma_f32 v[80:81], v[104:105], v[156:157], v[80:81]
	v_pk_fma_f32 v[80:81], v[108:109], v[192:193], v[80:81]
	v_pk_fma_f32 v[80:81], v[60:61], v[164:165], v[80:81]
	v_pk_mul_f32 v[82:83], v[80:81], v[250:251] op_sel_hi:[1,0]
	v_exp_f32_e32 v82, v82
	v_exp_f32_e32 v83, v83
	s_nop 0
	v_pk_add_f32 v[82:83], v[82:83], 1.0 op_sel_hi:[1,0]
	v_rcp_f32_e32 v83, v83
	v_rcp_f32_e32 v82, v82
	s_nop 0
	v_pk_mul_f32 v[146:147], v[80:81], v[82:83]
	v_pk_fma_f32 v[80:81], v[102:103], v[174:175], v[114:115]
	v_pk_fma_f32 v[80:81], v[106:107], v[170:171], v[80:81]
	v_pk_fma_f32 v[80:81], v[110:111], v[154:155], v[80:81]
	v_pk_fma_f32 v[80:81], v[62:63], v[188:189], v[80:81]
	v_pk_mul_f32 v[82:83], v[80:81], v[250:251] op_sel_hi:[1,0]
	v_exp_f32_e32 v82, v82
	v_exp_f32_e32 v83, v83
	s_nop 0
	v_pk_add_f32 v[82:83], v[82:83], 1.0 op_sel_hi:[1,0]
	v_rcp_f32_e32 v83, v83
	v_rcp_f32_e32 v82, v82
	s_nop 0
	v_pk_mul_f32 v[148:149], v[80:81], v[82:83]
	v_pk_fma_f32 v[80:81], v[102:103], v[170:171], v[114:115]
	v_pk_fma_f32 v[80:81], v[106:107], v[154:155], v[80:81]
	v_pk_fma_f32 v[80:81], v[110:111], v[188:189], v[80:81]
	v_pk_fma_f32 v[80:81], v[62:63], v[162:163], v[80:81]
	v_pk_mul_f32 v[82:83], v[80:81], v[250:251] op_sel_hi:[1,0]
	v_exp_f32_e32 v82, v82
	v_exp_f32_e32 v83, v83
	s_nop 0
	v_pk_add_f32 v[82:83], v[82:83], 1.0 op_sel_hi:[1,0]
	v_rcp_f32_e32 v83, v83
	v_rcp_f32_e32 v82, v82
	s_nop 0
	v_pk_mul_f32 v[150:151], v[80:81], v[82:83]
	v_pk_fma_f32 v[80:81], v[44:45], v[168:169], v[56:57]
	v_pk_fma_f32 v[80:81], v[48:49], v[96:97], v[80:81]
	v_pk_fma_f32 v[80:81], v[52:53], v[152:153], v[80:81]
	v_pk_fma_f32 v[80:81], v[40:41], v[172:173], v[80:81]
	v_pk_mul_f32 v[82:83], v[80:81], v[250:251] op_sel_hi:[1,0]
	v_exp_f32_e32 v82, v82
	v_exp_f32_e32 v83, v83
	s_nop 0
	v_pk_add_f32 v[82:83], v[82:83], 1.0 op_sel_hi:[1,0]
	v_rcp_f32_e32 v83, v83
	v_rcp_f32_e32 v82, v82
	s_nop 0
	v_pk_mul_f32 v[158:159], v[80:81], v[82:83]
	v_pk_fma_f32 v[80:81], v[44:45], v[96:97], v[56:57]
	v_pk_fma_f32 v[80:81], v[48:49], v[152:153], v[80:81]
	v_pk_fma_f32 v[80:81], v[52:53], v[172:173], v[80:81]
	v_pk_fma_f32 v[80:81], v[40:41], v[128:129], v[80:81]
	v_pk_mul_f32 v[82:83], v[80:81], v[250:251] op_sel_hi:[1,0]
	v_exp_f32_e32 v82, v82
	v_exp_f32_e32 v83, v83
	s_nop 0
	v_pk_add_f32 v[82:83], v[82:83], 1.0 op_sel_hi:[1,0]
	v_rcp_f32_e32 v83, v83
	v_rcp_f32_e32 v82, v82
	s_nop 0
	v_pk_mul_f32 v[166:167], v[80:81], v[82:83]
	v_pk_fma_f32 v[80:81], v[46:47], v[94:95], v[58:59]
	v_pk_fma_f32 v[80:81], v[50:51], v[92:93], v[80:81]
	v_pk_fma_f32 v[80:81], v[54:55], v[120:121], v[80:81]
	v_pk_fma_f32 v[80:81], v[42:43], v[122:123], v[80:81]
	v_pk_mul_f32 v[82:83], v[80:81], v[250:251] op_sel_hi:[1,0]
	v_exp_f32_e32 v82, v82
	v_exp_f32_e32 v83, v83
	s_nop 0
	v_pk_add_f32 v[82:83], v[82:83], 1.0 op_sel_hi:[1,0]
	v_rcp_f32_e32 v83, v83
	v_rcp_f32_e32 v82, v82
	s_nop 0
	v_pk_mul_f32 v[184:185], v[80:81], v[82:83]
	v_pk_fma_f32 v[80:81], v[46:47], v[92:93], v[58:59]
	v_pk_fma_f32 v[80:81], v[50:51], v[120:121], v[80:81]
	v_pk_fma_f32 v[80:81], v[54:55], v[122:123], v[80:81]
	v_pk_fma_f32 v[80:81], v[42:43], v[124:125], v[80:81]
	v_pk_mul_f32 v[82:83], v[80:81], v[250:251] op_sel_hi:[1,0]
	v_exp_f32_e32 v82, v82
	v_exp_f32_e32 v83, v83
	s_nop 0
	v_pk_add_f32 v[82:83], v[82:83], 1.0 op_sel_hi:[1,0]
	v_rcp_f32_e32 v83, v83
	v_rcp_f32_e32 v82, v82
	s_nop 0
	v_pk_mul_f32 v[194:195], v[80:81], v[82:83]

; DI float lo16(unsigned w) { return __uint_as_float(w << 16); }
; DI float hi16(unsigned w) { return __uint_as_float(w & 0xffff0000u); }
; DI void conv_row8(const u32x4 (&raw)[11], int i, const float (&w)[4][8], const float (&bias)[8], float (&v)[8]) {
; #pragma unroll
;     for (int e = 0; e < 8; ++e) v[e] = bias[e];
; #pragma unroll
;     for (int jj = 0; jj < 4; ++jj) {
; #pragma unroll
;         for (int e = 0; e < 4; ++e) { v[2 * e] += w[jj][2 * e] * lo16(raw[i + jj][e]); v[2 * e + 1] += w[jj][2 * e + 1] * hi16(raw[i + jj][e]); }
;     }
; #pragma unroll
;     for (int e = 0; e < 8; ++e) v[e] = v[e] * __frcp_rn(1.0f + __expf(-v[e]));
; }
; DI void ssd_prompt_unit(const Args& a, int b, int hd, LAS unsigned char* lds, const int tid) {
;     ...
;             for (int k = 0; k < 4; ++k) {
;                 const bool act = stager || k == 0;
;                 float va[8], vb[8];
;                 if (act) { conv_row8(raw, 2 * k, cwt, cbias, va); conv_row8(raw, 2 * k + 1, cwt, cbias, vb); }
;                 raw[2 * k] = *(const u32x4*)(nsrc + SP_ROWOFF(2 * k)); raw[2 * k + 1] = *(const u32x4*)(nsrc + SP_ROWOFF(2 * k + 1));
.LBB0_308:
	s_and_b64 vcc, exec, s[52:53]
	v_lshlrev_b32_e32 v174, 16, v84
	v_and_b32_e32 v175, 0xffff0000, v84
	v_lshlrev_b32_e32 v186, 16, v88
	v_and_b32_e32 v187, 0xffff0000, v88
	v_lshlrev_b32_e32 v168, 16, v85
	v_and_b32_e32 v169, 0xffff0000, v85
	v_lshlrev_b32_e32 v170, 16, v89
	v_and_b32_e32 v171, 0xffff0000, v89
	v_lshlrev_b32_e32 v126, 16, v86
	v_and_b32_e32 v127, 0xffff0000, v86
	v_lshlrev_b32_e32 v130, 16, v90
	v_and_b32_e32 v131, 0xffff0000, v90
	v_lshlrev_b32_e32 v116, 16, v87
	v_and_b32_e32 v117, 0xffff0000, v87
	v_lshlrev_b32_e32 v118, 16, v91
	v_and_b32_e32 v119, 0xffff0000, v91
	s_cbranch_vccnz .LBB0_310
	v_pk_fma_f32 v[80:81], v[100:101], v[156:157], v[112:113]
	v_pk_fma_f32 v[80:81], v[104:105], v[192:193], v[80:81]
	v_pk_fma_f32 v[80:81], v[108:109], v[164:165], v[80:81]
	v_pk_fma_f32 v[80:81], v[60:61], v[174:175], v[80:81]
	v_pk_mul_f32 v[82:83], v[80:81], v[250:251] op_sel_hi:[1,0]
	v_exp_f32_e32 v82, v82
	v_exp_f32_e32 v83, v83
	s_nop 0
	v_pk_add_f32 v[82:83], v[82:83], 1.0 op_sel_hi:[1,0]
	v_rcp_f32_e32 v83, v83
	v_rcp_f32_e32 v82, v82
	s_nop 0
	v_pk_mul_f32 v[144:145], v[80:81], v[82:83]
	v_pk_fma_f32 v[80:81], v[100:101], v[192:193], v[112:113]
	v_pk_fma_f32 v[80:81], v[104:105], v[164:165], v[80:81]
	v_pk_fma_f32 v[80:81], v[108:109], v[174:175], v[80:81]
	v_pk_fma_f32 v[80:81], v[60:61], v[186:187], v[80:81]
	v_pk_mul_f32 v[82:83], v[80:81], v[250:251] op_sel_hi:[1,0]
	v_exp_f32_e32 v82, v82
	v_exp_f32_e32 v83, v83
	s_nop 0
	v_pk_add_f32 v[82:83], v[82:83], 1.0 op_sel_hi:[1,0]
	v_rcp_f32_e32 v83, v83
	v_rcp_f32_e32 v82, v82
	s_nop 0
	v_pk_mul_f32 v[146:147], v[80:81], v[82:83]
	v_pk_fma_f32 v[80:81], v[102:103], v[154:155], v[114:115]
	v_pk_fma_f32 v[80:81], v[106:107], v[188:189], v[80:81]
	v_pk_fma_f32 v[80:81], v[110:111], v[162:163], v[80:81]
	v_pk_fma_f32 v[80:81], v[62:63], v[168:169], v[80:81]
	v_pk_mul_f32 v[82:83], v[80:81], v[250:251] op_sel_hi:[1,0]
	v_exp_f32_e32 v82, v82
	v_exp_f32_e32 v83, v83
	s_nop 0
	v_pk_add_f32 v[82:83], v[82:83], 1.0 op_sel_hi:[1,0]
	v_rcp_f32_e32 v83, v83
	v_rcp_f32_e32 v82, v82
	s_nop 0
	v_pk_mul_f32 v[148:149], v[80:81], v[82:83]
	v_pk_fma_f32 v[80:81], v[102:103], v[188:189], v[114:115]
	v_pk_fma_f32 v[80:81], v[106:107], v[162:163], v[80:81]
	v_pk_fma_f32 v[80:81], v[110:111], v[168:169], v[80:81]
	v_pk_fma_f32 v[80:81], v[62:63], v[170:171], v[80:81]
	v_pk_mul_f32 v[82:83], v[80:81], v[250:251] op_sel_hi:[1,0]
	v_exp_f32_e32 v82, v82
	v_exp_f32_e32 v83, v83
	s_nop 0
	v_pk_add_f32 v[82:83], v[82:83], 1.0 op_sel_hi:[1,0]
	v_rcp_f32_e32 v83, v83
	v_rcp_f32_e32 v82, v82
	s_nop 0
	v_pk_mul_f32 v[150:151], v[80:81], v[82:83]
	v_pk_fma_f32 v[80:81], v[44:45], v[152:153], v[56:57]
	v_pk_fma_f32 v[80:81], v[48:49], v[172:173], v[80:81]
	v_pk_fma_f32 v[80:81], v[52:53], v[128:129], v[80:81]
	v_pk_fma_f32 v[80:81], v[40:41], v[126:127], v[80:81]
	v_pk_mul_f32 v[82:83], v[80:81], v[250:251] op_sel_hi:[1,0]
	v_exp_f32_e32 v82, v82
	v_exp_f32_e32 v83, v83
	s_nop 0
	v_pk_add_f32 v[82:83], v[82:83], 1.0 op_sel_hi:[1,0]
	v_rcp_f32_e32 v83, v83
	v_rcp_f32_e32 v82, v82
	s_nop 0
	v_pk_mul_f32 v[158:159], v[80:81], v[82:83]
	v_pk_fma_f32 v[80:81], v[44:45], v[172:173], v[56:57]
	v_pk_fma_f32 v[80:81], v[48:49], v[128:129], v[80:81]
	v_pk_fma_f32 v[80:81], v[52:53], v[126:127], v[80:81]
	v_pk_fma_f32 v[80:81], v[40:41], v[130:131], v[80:81]
	v_pk_mul_f32 v[82:83], v[80:81], v[250:251] op_sel_hi:[1,0]
	v_exp_f32_e32 v82, v82
	v_exp_f32_e32 v83, v83
	s_nop 0
	v_pk_add_f32 v[82:83], v[82:83], 1.0 op_sel_hi:[1,0]
	v_rcp_f32_e32 v83, v83
	v_rcp_f32_e32 v82, v82
	s_nop 0
	v_pk_mul_f32 v[166:167], v[80:81], v[82:83]
	v_pk_fma_f32 v[80:81], v[46:47], v[120:121], v[58:59]
	v_pk_fma_f32 v[80:81], v[50:51], v[122:123], v[80:81]
	v_pk_fma_f32 v[80:81], v[54:55], v[124:125], v[80:81]
	v_pk_fma_f32 v[80:81], v[42:43], v[116:117], v[80:81]
	v_pk_mul_f32 v[82:83], v[80:81], v[250:251] op_sel_hi:[1,0]
	v_exp_f32_e32 v82, v82
	v_exp_f32_e32 v83, v83
	s_nop 0
	v_pk_add_f32 v[82:83], v[82:83], 1.0 op_sel_hi:[1,0]
	v_rcp_f32_e32 v83, v83
	v_rcp_f32_e32 v82, v82
	s_nop 0
	v_pk_mul_f32 v[184:185], v[80:81], v[82:83]
	v_pk_fma_f32 v[80:81], v[46:47], v[122:123], v[58:59]
	v_pk_fma_f32 v[80:81], v[50:51], v[124:125], v[80:81]
	v_pk_fma_f32 v[80:81], v[54:55], v[116:117], v[80:81]
	v_pk_fma_f32 v[80:81], v[42:43], v[118:119], v[80:81]
	v_pk_mul_f32 v[82:83], v[80:81], v[250:251] op_sel_hi:[1,0]
	v_exp_f32_e32 v82, v82
	v_exp_f32_e32 v83, v83
	s_nop 0
	v_pk_add_f32 v[82:83], v[82:83], 1.0 op_sel_hi:[1,0]
	v_rcp_f32_e32 v83, v83
	v_rcp_f32_e32 v82, v82
	s_nop 0
	v_pk_mul_f32 v[194:195], v[80:81], v[82:83]

; DI float lo16(unsigned w) { return __uint_as_float(w << 16); }
; DI float hi16(unsigned w) { return __uint_as_float(w & 0xffff0000u); }
; DI void conv_row8(const u32x4 (&raw)[11], int i, const float (&w)[4][8], const float (&bias)[8], float (&v)[8]) {
; #pragma unroll
;     for (int e = 0; e < 8; ++e) v[e] = bias[e];
; #pragma unroll
;     for (int jj = 0; jj < 4; ++jj) {
; #pragma unroll
;         for (int e = 0; e < 4; ++e) { v[2 * e] += w[jj][2 * e] * lo16(raw[i + jj][e]); v[2 * e + 1] += w[jj][2 * e + 1] * hi16(raw[i + jj][e]); }
;     }
; #pragma unroll
;     for (int e = 0; e < 8; ++e) v[e] = v[e] * __frcp_rn(1.0f + __expf(-v[e]));
; }
; DI void ssd_prompt_unit(const Args& a, int b, int hd, LAS unsigned char* lds, const int tid) {
;     ...
;             for (int k = 0; k < 4; ++k) {
;                 const bool act = stager || k == 0;
;                 float va[8], vb[8];
;                 if (act) { conv_row8(raw, 2 * k, cwt, cbias, va); conv_row8(raw, 2 * k + 1, cwt, cbias, vb); }
;                 raw[2 * k] = *(const u32x4*)(nsrc + SP_ROWOFF(2 * k)); raw[2 * k + 1] = *(const u32x4*)(nsrc + SP_ROWOFF(2 * k + 1));
;                 if (k == 3) { raw[8] = *(const u32x4*)(nsrc + SP_ROWOFF(8)); raw[9] = *(const u32x4*)(nsrc + SP_ROWOFF(9)); raw[10] = *(const u32x4*)(nsrc + SP_ROWOFF(10)); }
.LBB0_319:
	s_and_b64 vcc, exec, s[52:53]
	s_cbranch_vccnz .LBB0_321
	v_pk_fma_f32 v[36:37], v[100:101], v[164:165], v[112:113]
	s_waitcnt lgkmcnt(0)
	v_lshlrev_b32_e32 v32, 16, v68
	v_pk_fma_f32 v[36:37], v[104:105], v[174:175], v[36:37]
	v_and_b32_e32 v33, 0xffff0000, v68
	v_pk_fma_f32 v[36:37], v[108:109], v[186:187], v[36:37]
	v_pk_fma_f32 v[36:37], v[60:61], v[32:33], v[36:37]
	v_mul_f32_e32 v68, 0xbfb8aa3b, v36
	v_exp_f32_e32 v84, v68
	v_mul_f32_e32 v68, 0xbfb8aa3b, v37
	v_exp_f32_e32 v85, v68
	s_nop 0
	v_pk_add_f32 v[84:85], v[84:85], 1.0 op_sel_hi:[1,0]
	v_rcp_f32_e32 v85, v85
	v_rcp_f32_e32 v84, v84
	s_nop 0
	v_pk_mul_f32 v[144:145], v[36:37], v[84:85]
	v_pk_fma_f32 v[36:37], v[100:101], v[174:175], v[112:113]
	v_pk_fma_f32 v[36:37], v[104:105], v[186:187], v[36:37]
	v_pk_fma_f32 v[32:33], v[108:109], v[32:33], v[36:37]
	v_lshlrev_b32_e32 v36, 16, v64
	v_and_b32_e32 v37, 0xffff0000, v64
	v_pk_fma_f32 v[32:33], v[60:61], v[36:37], v[32:33]
	v_pk_mul_f32 v[36:37], v[32:33], v[250:251] op_sel_hi:[1,0]
	v_exp_f32_e32 v36, v36
	v_exp_f32_e32 v37, v37
	s_nop 0
	v_pk_add_f32 v[36:37], v[36:37], 1.0 op_sel_hi:[1,0]
	v_rcp_f32_e32 v37, v37
	v_rcp_f32_e32 v36, v36
	s_nop 0
	v_pk_mul_f32 v[146:147], v[32:33], v[36:37]
	v_pk_fma_f32 v[36:37], v[102:103], v[162:163], v[114:115]
	v_lshlrev_b32_e32 v32, 16, v69
	v_pk_fma_f32 v[36:37], v[106:107], v[168:169], v[36:37]
	v_and_b32_e32 v33, 0xffff0000, v69
	v_pk_fma_f32 v[36:37], v[110:111], v[170:171], v[36:37]
	v_pk_fma_f32 v[36:37], v[62:63], v[32:33], v[36:37]
	v_pk_mul_f32 v[60:61], v[36:37], v[250:251] op_sel_hi:[1,0]
	v_exp_f32_e32 v60, v60
	v_exp_f32_e32 v61, v61
	s_nop 0
	v_pk_add_f32 v[60:61], v[60:61], 1.0 op_sel_hi:[1,0]
	v_rcp_f32_e32 v61, v61
	v_rcp_f32_e32 v60, v60
	s_nop 0
	v_pk_mul_f32 v[148:149], v[36:37], v[60:61]
	v_pk_fma_f32 v[36:37], v[102:103], v[168:169], v[114:115]
	v_pk_fma_f32 v[36:37], v[106:107], v[170:171], v[36:37]
	v_pk_fma_f32 v[32:33], v[110:111], v[32:33], v[36:37]
	v_lshlrev_b32_e32 v36, 16, v65
	v_and_b32_e32 v37, 0xffff0000, v65
	v_pk_fma_f32 v[32:33], v[62:63], v[36:37], v[32:33]
	v_pk_mul_f32 v[36:37], v[32:33], v[250:251] op_sel_hi:[1,0]
	v_exp_f32_e32 v36, v36
	v_exp_f32_e32 v37, v37
	s_nop 0
	v_pk_add_f32 v[36:37], v[36:37], 1.0 op_sel_hi:[1,0]
	v_rcp_f32_e32 v37, v37
	v_rcp_f32_e32 v36, v36
	s_nop 0
	v_pk_mul_f32 v[150:151], v[32:33], v[36:37]
	v_pk_fma_f32 v[36:37], v[44:45], v[128:129], v[56:57]
	v_lshlrev_b32_e32 v32, 16, v70
	v_pk_fma_f32 v[36:37], v[48:49], v[126:127], v[36:37]
	v_and_b32_e32 v33, 0xffff0000, v70
	v_pk_fma_f32 v[36:37], v[52:53], v[130:131], v[36:37]
	v_pk_fma_f32 v[36:37], v[40:41], v[32:33], v[36:37]
	v_pk_mul_f32 v[60:61], v[36:37], v[250:251] op_sel_hi:[1,0]
	v_exp_f32_e32 v60, v60
	v_exp_f32_e32 v61, v61
	s_nop 0
	v_pk_add_f32 v[60:61], v[60:61], 1.0 op_sel_hi:[1,0]
	v_rcp_f32_e32 v61, v61
	v_rcp_f32_e32 v60, v60
	s_nop 0
	v_pk_mul_f32 v[158:159], v[36:37], v[60:61]
	v_pk_fma_f32 v[36:37], v[44:45], v[126:127], v[56:57]
	v_pk_fma_f32 v[36:37], v[48:49], v[130:131], v[36:37]
	v_pk_fma_f32 v[32:33], v[52:53], v[32:33], v[36:37]
	v_lshlrev_b32_e32 v36, 16, v66
	v_and_b32_e32 v37, 0xffff0000, v66
	v_pk_fma_f32 v[32:33], v[40:41], v[36:37], v[32:33]
	v_pk_mul_f32 v[36:37], v[32:33], v[250:251] op_sel_hi:[1,0]
	v_exp_f32_e32 v36, v36
	v_exp_f32_e32 v37, v37
	s_nop 0
	v_pk_add_f32 v[36:37], v[36:37], 1.0 op_sel_hi:[1,0]
	v_rcp_f32_e32 v37, v37
	v_rcp_f32_e32 v36, v36
	s_nop 0
	v_pk_mul_f32 v[166:167], v[32:33], v[36:37]
	v_pk_fma_f32 v[36:37], v[46:47], v[124:125], v[58:59]
	v_lshlrev_b32_e32 v32, 16, v71
	v_pk_fma_f32 v[36:37], v[50:51], v[116:117], v[36:37]
	v_and_b32_e32 v33, 0xffff0000, v71
	v_pk_fma_f32 v[36:37], v[54:55], v[118:119], v[36:37]
	v_pk_fma_f32 v[36:37], v[42:43], v[32:33], v[36:37]
	v_pk_mul_f32 v[40:41], v[36:37], v[250:251] op_sel_hi:[1,0]
	v_exp_f32_e32 v40, v40
	v_exp_f32_e32 v41, v41
	s_nop 0
	v_pk_add_f32 v[40:41], v[40:41], 1.0 op_sel_hi:[1,0]
	v_rcp_f32_e32 v41, v41
	v_rcp_f32_e32 v40, v40
	s_nop 0
	v_pk_mul_f32 v[184:185], v[36:37], v[40:41]
	v_pk_fma_f32 v[36:37], v[46:47], v[116:117], v[58:59]
	v_pk_fma_f32 v[36:37], v[50:51], v[118:119], v[36:37]
	v_pk_fma_f32 v[32:33], v[54:55], v[32:33], v[36:37]
	v_lshlrev_b32_e32 v36, 16, v67
	v_and_b32_e32 v37, 0xffff0000, v67
	v_pk_fma_f32 v[32:33], v[42:43], v[36:37], v[32:33]
	v_pk_mul_f32 v[36:37], v[32:33], v[250:251] op_sel_hi:[1,0]
	v_exp_f32_e32 v36, v36
	v_exp_f32_e32 v37, v37
	s_nop 0
	v_pk_add_f32 v[36:37], v[36:37], 1.0 op_sel_hi:[1,0]
	v_rcp_f32_e32 v37, v37
	v_rcp_f32_e32 v36, v36
	s_nop 0
	v_pk_mul_f32 v[194:195], v[32:33], v[36:37]
